# attention-A item epilogue: the 15 serialized gate loads (load, wait, use, next load) issued together up front with one counted wait per use
# speedup vs baseline: 1.0056x; 1.0056x over previous
; #define GAS __attribute__((address_space(1)))
; __device__ __forceinline__ unsigned cvt_pk_bf16(float lo, float hi) { unsigned r; asm volatile("v_cvt_pk_bf16_f32 %0, %1, %2" : "=v"(r) : "v"(lo), "v"(hi)); return r; }
; __device__ __forceinline__ float bflo(unsigned w) { return __uint_as_float(w << 16); }
; __device__ __forceinline__ float bfhi(unsigned w) { return __uint_as_float(w & 0xffff0000u); }
; template <int MODE>
; __device__ void attn_block(LAS unsigned char* lds, const bf16_t* Qp, const bf16_t* Kp, const bf16_t* Vp, int qb, const unsigned* maskp, const bf16_t* sga, bf16_t* outp, const float negMB) {
;     ...
;     const float ltot = lrun + __shfl_xor(lrun, 32);
;     const float inv = 1.0f / ltot;
; #pragma unroll
;     for (int d = 0; d < 4; ++d)
; #pragma unroll
;         for (int g = 0; g < 4; ++g) {
;             const int dd = 32 * d + 8 * g + 4 * h;
;             float v0 = o[d][4 * g] * inv, v1 = o[d][4 * g + 1] * inv, v2 = o[d][4 * g + 2] * inv, v3 = o[d][4 * g + 3] * inv;
;             if (MODE == 0) {
;                 const u32x2 gw = *(const GAS u32x2*)(sga + (size_t)qpos * 1024 + dd);
;                 v0 *= bflo(gw.x); v1 *= bfhi(gw.x); v2 *= bflo(gw.y); v3 *= bfhi(gw.y);
;                 u32x2 w; w.x = cvt_pk_bf16(v0, v1); w.y = cvt_pk_bf16(v2, v3);
;                 *(GAS u32x2*)(outp + (size_t)qpos * 2048 + dd) = w;
;             } else {
;                 u32x2 w; w.x = cvt_pk_bf16(v0, v1); w.y = cvt_pk_bf16(v2, v3);
;                 *(GAS u32x2*)(outp + (size_t)qpos * 2048 + dd) = w;
;             }
;         }
.LBB0_882:
	s_lshl_b32 s4, s48, 1
	s_add_u32 s4, s6, s4
	s_addc_u32 s5, s7, 0
	s_add_u32 s4, s4, s45
	s_addc_u32 s5, s5, 0
	v_lshl_add_u64 v[2:3], s[4:5], 0, v[172:173]
	v_lshlrev_b32_e32 v0, 1, v168
	v_lshl_add_u64 v[2:3], v[2:3], 0, v[0:1]
	v_add_co_u32_e32 v4, vcc, s40, v2
	ds_bpermute_b32 v6, v184, v193
	s_nop 0
	v_addc_co_u32_e32 v5, vcc, 0, v3, vcc
	global_load_dwordx2 v[4:5], v[4:5], off
	v_lshl_add_u64 v[2:3], v[2:3], 0, s[20:21]
	global_load_dwordx2 v[96:97], v[2:3], off offset:16
	global_load_dwordx2 v[98:99], v[2:3], off offset:32
	global_load_dwordx2 v[100:101], v[2:3], off offset:48
	global_load_dwordx2 v[102:103], v[2:3], off offset:64
	global_load_dwordx2 v[104:105], v[2:3], off offset:80
	global_load_dwordx2 v[106:107], v[2:3], off offset:96
	global_load_dwordx2 v[108:109], v[2:3], off offset:112
	global_load_dwordx2 v[110:111], v[2:3], off offset:128
	global_load_dwordx2 v[112:113], v[2:3], off offset:144
	global_load_dwordx2 v[114:115], v[2:3], off offset:160
	global_load_dwordx2 v[116:117], v[2:3], off offset:176
	global_load_dwordx2 v[118:119], v[2:3], off offset:192
	global_load_dwordx2 v[120:121], v[2:3], off offset:208
	global_load_dwordx2 v[122:123], v[2:3], off offset:224
	global_load_dwordx2 v[124:125], v[2:3], off offset:240
	s_waitcnt lgkmcnt(0)
	v_add_f32_e32 v6, v193, v6
	v_div_scale_f32 v7, s[4:5], v6, v6, 1.0
	v_rcp_f32_e32 v8, v7
	v_div_scale_f32 v9, vcc, 1.0, v6, 1.0
	s_lshl_b32 s4, s44, 12
	v_fma_f32 v10, -v7, v8, 1.0
	v_fmac_f32_e32 v8, v10, v8
	v_mul_f32_e32 v10, v9, v8
	v_fma_f32 v11, -v7, v10, v9
	v_fmac_f32_e32 v10, v11, v8
	v_fma_f32 v7, -v7, v10, v9
	v_div_fmas_f32 v7, v7, v8, v10
	v_div_fixup_f32 v12, v7, v6, 1.0
	v_mul_f32_e32 v6, v80, v12
	v_mul_f32_e32 v7, v81, v12
	v_mul_f32_e32 v8, v82, v12
	v_mul_f32_e32 v9, v83, v12
	s_add_u32 s4, s6, s4
	s_addc_u32 s5, s7, 0
	s_add_u32 s4, s4, s45
	s_addc_u32 s5, s5, 0
	v_mul_f32_e32 v15, v87, v12
	v_mul_f32_e32 v13, v85, v12
	v_mul_f32_e32 v14, v86, v12
	s_waitcnt vmcnt(15)
	v_lshlrev_b32_e32 v10, 16, v4
	v_and_b32_e32 v4, 0xffff0000, v4
	v_lshlrev_b32_e32 v11, 16, v5
	v_and_b32_e32 v5, 0xffff0000, v5
	v_mul_f32_e32 v6, v6, v10
	v_mul_f32_e32 v4, v7, v4
	v_mul_f32_e32 v7, v8, v11
	v_mul_f32_e32 v5, v9, v5
	v_cvt_pk_bf16_f32 v4, v6, v4
	v_cvt_pk_bf16_f32 v5, v7, v5
	v_lshlrev_b64 v[8:9], 12, v[170:171]
	v_lshl_add_u64 v[8:9], s[4:5], 0, v[8:9]
	v_lshl_add_u64 v[8:9], v[8:9], 0, v[0:1]
	v_add_co_u32_e32 v10, vcc, s41, v8
	v_mul_f32_e32 v0, v84, v12
	s_nop 0
	v_addc_co_u32_e32 v11, vcc, 0, v9, vcc
	global_store_dwordx2 v[10:11], v[4:5], off
	s_waitcnt vmcnt(15)
	v_mov_b32_e32 v6, v96
	v_mov_b32_e32 v7, v97
	v_lshlrev_b32_e32 v4, 16, v6
	v_and_b32_e32 v5, 0xffff0000, v6
	v_lshlrev_b32_e32 v6, 16, v7
	v_and_b32_e32 v7, 0xffff0000, v7
	v_mul_f32_e32 v7, v15, v7
	v_mul_f32_e32 v0, v0, v4
	v_mul_f32_e32 v4, v13, v5
	v_mul_f32_e32 v5, v14, v6
	v_cvt_pk_bf16_f32 v6, v0, v4
	v_cvt_pk_bf16_f32 v7, v5, v7
	v_lshl_add_u64 v[4:5], v[8:9], 0, s[22:23]
	v_mul_f32_e32 v0, v88, v12
	v_mul_f32_e32 v8, v89, v12
	v_mul_f32_e32 v9, v90, v12
	v_mul_f32_e32 v13, v91, v12
	global_store_dwordx2 v[4:5], v[6:7], off offset:16
	s_waitcnt vmcnt(15)
	v_mov_b32_e32 v10, v98
	v_mov_b32_e32 v11, v99
	v_lshlrev_b32_e32 v6, 16, v10
	v_and_b32_e32 v7, 0xffff0000, v10
	v_lshlrev_b32_e32 v10, 16, v11
	v_and_b32_e32 v11, 0xffff0000, v11
	v_mul_f32_e32 v0, v0, v6
	v_mul_f32_e32 v6, v8, v7
	v_mul_f32_e32 v7, v9, v10
	v_mul_f32_e32 v8, v13, v11
	v_cvt_pk_bf16_f32 v6, v0, v6
	v_cvt_pk_bf16_f32 v7, v7, v8
	v_mul_f32_e32 v0, v92, v12
	v_mul_f32_e32 v10, v93, v12
	v_mul_f32_e32 v11, v94, v12
	v_mul_f32_e32 v13, v95, v12
	global_store_dwordx2 v[4:5], v[6:7], off offset:32
	s_waitcnt vmcnt(15)
	v_mov_b32_e32 v8, v100
	v_mov_b32_e32 v9, v101
	v_lshlrev_b32_e32 v6, 16, v8
	v_and_b32_e32 v7, 0xffff0000, v8
	v_lshlrev_b32_e32 v8, 16, v9
	v_and_b32_e32 v9, 0xffff0000, v9
	v_mul_f32_e32 v0, v0, v6
	v_mul_f32_e32 v6, v10, v7
	v_mul_f32_e32 v7, v11, v8
	v_mul_f32_e32 v8, v13, v9
	v_cvt_pk_bf16_f32 v6, v0, v6
	v_cvt_pk_bf16_f32 v7, v7, v8
	v_mul_f32_e32 v0, v64, v12
	v_mul_f32_e32 v10, v65, v12
	v_mul_f32_e32 v11, v66, v12
	v_mul_f32_e32 v13, v67, v12
	global_store_dwordx2 v[4:5], v[6:7], off offset:48
	s_waitcnt vmcnt(15)
	v_mov_b32_e32 v8, v102
	v_mov_b32_e32 v9, v103
	v_lshlrev_b32_e32 v6, 16, v8
	v_and_b32_e32 v7, 0xffff0000, v8
	v_lshlrev_b32_e32 v8, 16, v9
	v_and_b32_e32 v9, 0xffff0000, v9
	v_mul_f32_e32 v0, v0, v6
	v_mul_f32_e32 v6, v10, v7
	v_mul_f32_e32 v7, v11, v8
	v_mul_f32_e32 v8, v13, v9
	v_cvt_pk_bf16_f32 v6, v0, v6
	v_cvt_pk_bf16_f32 v7, v7, v8
	v_mul_f32_e32 v0, v68, v12
	v_mul_f32_e32 v10, v69, v12
	v_mul_f32_e32 v11, v70, v12
	v_mul_f32_e32 v13, v71, v12
	global_store_dwordx2 v[4:5], v[6:7], off offset:64
	s_waitcnt vmcnt(15)
	v_mov_b32_e32 v8, v104
	v_mov_b32_e32 v9, v105
	v_lshlrev_b32_e32 v6, 16, v8
	v_and_b32_e32 v7, 0xffff0000, v8
	v_lshlrev_b32_e32 v8, 16, v9
	v_and_b32_e32 v9, 0xffff0000, v9
	v_mul_f32_e32 v0, v0, v6
	v_mul_f32_e32 v6, v10, v7
	v_mul_f32_e32 v7, v11, v8
	v_mul_f32_e32 v8, v13, v9
	v_cvt_pk_bf16_f32 v6, v0, v6
	v_cvt_pk_bf16_f32 v7, v7, v8
	v_mul_f32_e32 v0, v72, v12
	v_mul_f32_e32 v10, v73, v12
	v_mul_f32_e32 v11, v74, v12
	v_mul_f32_e32 v13, v75, v12
	global_store_dwordx2 v[4:5], v[6:7], off offset:80
	s_waitcnt vmcnt(15)
; #define GAS __attribute__((address_space(1)))
; __device__ __forceinline__ unsigned cvt_pk_bf16(float lo, float hi) { unsigned r; asm volatile("v_cvt_pk_bf16_f32 %0, %1, %2" : "=v"(r) : "v"(lo), "v"(hi)); return r; }
; __device__ __forceinline__ float bflo(unsigned w) { return __uint_as_float(w << 16); }
; __device__ __forceinline__ float bfhi(unsigned w) { return __uint_as_float(w & 0xffff0000u); }
; template <int MODE>
; __device__ void attn_block(LAS unsigned char* lds, const bf16_t* Qp, const bf16_t* Kp, const bf16_t* Vp, int qb, const unsigned* maskp, const bf16_t* sga, bf16_t* outp, const float negMB) {
;     ...
;     for (int d = 0; d < 4; ++d)
; #pragma unroll
;         for (int g = 0; g < 4; ++g) {
;             const int dd = 32 * d + 8 * g + 4 * h;
;             float v0 = o[d][4 * g] * inv, v1 = o[d][4 * g + 1] * inv, v2 = o[d][4 * g + 2] * inv, v3 = o[d][4 * g + 3] * inv;
;             if (MODE == 0) {
;                 const u32x2 gw = *(const GAS u32x2*)(sga + (size_t)qpos * 1024 + dd);
;                 v0 *= bflo(gw.x); v1 *= bfhi(gw.x); v2 *= bflo(gw.y); v3 *= bfhi(gw.y);
;                 u32x2 w; w.x = cvt_pk_bf16(v0, v1); w.y = cvt_pk_bf16(v2, v3);
;                 *(GAS u32x2*)(outp + (size_t)qpos * 2048 + dd) = w;
;             } else {
;                 u32x2 w; w.x = cvt_pk_bf16(v0, v1); w.y = cvt_pk_bf16(v2, v3);
;                 *(GAS u32x2*)(outp + (size_t)qpos * 2048 + dd) = w;
;             }
;         }
	v_mov_b32_e32 v8, v106
	v_mov_b32_e32 v9, v107
	v_lshlrev_b32_e32 v6, 16, v8
	v_and_b32_e32 v7, 0xffff0000, v8
	v_lshlrev_b32_e32 v8, 16, v9
	v_and_b32_e32 v9, 0xffff0000, v9
	v_mul_f32_e32 v0, v0, v6
	v_mul_f32_e32 v6, v10, v7
	v_mul_f32_e32 v7, v11, v8
	v_mul_f32_e32 v8, v13, v9
	v_cvt_pk_bf16_f32 v6, v0, v6
	v_cvt_pk_bf16_f32 v7, v7, v8
	v_mul_f32_e32 v0, v76, v12
	v_mul_f32_e32 v10, v77, v12
	v_mul_f32_e32 v11, v78, v12
	v_mul_f32_e32 v13, v79, v12
	global_store_dwordx2 v[4:5], v[6:7], off offset:96
	s_waitcnt vmcnt(15)
	v_mov_b32_e32 v8, v108
	v_mov_b32_e32 v9, v109
	v_lshlrev_b32_e32 v6, 16, v8
	v_and_b32_e32 v7, 0xffff0000, v8
	v_lshlrev_b32_e32 v8, 16, v9
	v_and_b32_e32 v9, 0xffff0000, v9
	v_mul_f32_e32 v0, v0, v6
	v_mul_f32_e32 v6, v10, v7
	v_mul_f32_e32 v7, v11, v8
	v_mul_f32_e32 v8, v13, v9
	v_cvt_pk_bf16_f32 v6, v0, v6
	v_cvt_pk_bf16_f32 v7, v7, v8
	v_mul_f32_e32 v0, v48, v12
	v_mul_f32_e32 v10, v49, v12
	v_mul_f32_e32 v11, v50, v12
	v_mul_f32_e32 v13, v51, v12
	global_store_dwordx2 v[4:5], v[6:7], off offset:112
	s_waitcnt vmcnt(15)
	v_mov_b32_e32 v8, v110
	v_mov_b32_e32 v9, v111
	v_lshlrev_b32_e32 v6, 16, v8
	v_and_b32_e32 v7, 0xffff0000, v8
	v_lshlrev_b32_e32 v8, 16, v9
	v_and_b32_e32 v9, 0xffff0000, v9
	v_mul_f32_e32 v0, v0, v6
	v_mul_f32_e32 v6, v10, v7
	v_mul_f32_e32 v7, v11, v8
	v_mul_f32_e32 v8, v13, v9
	v_cvt_pk_bf16_f32 v6, v0, v6
	v_cvt_pk_bf16_f32 v7, v7, v8
	v_mul_f32_e32 v0, v52, v12
	v_mul_f32_e32 v10, v53, v12
	v_mul_f32_e32 v11, v54, v12
	v_mul_f32_e32 v13, v55, v12
	global_store_dwordx2 v[4:5], v[6:7], off offset:128
	s_waitcnt vmcnt(15)
	v_mov_b32_e32 v8, v112
	v_mov_b32_e32 v9, v113
	v_lshlrev_b32_e32 v6, 16, v8
	v_and_b32_e32 v7, 0xffff0000, v8
	v_lshlrev_b32_e32 v8, 16, v9
	v_and_b32_e32 v9, 0xffff0000, v9
	v_mul_f32_e32 v0, v0, v6
	v_mul_f32_e32 v6, v10, v7
	v_mul_f32_e32 v7, v11, v8
	v_mul_f32_e32 v8, v13, v9
	v_cvt_pk_bf16_f32 v6, v0, v6
	v_cvt_pk_bf16_f32 v7, v7, v8
	v_mul_f32_e32 v0, v56, v12
	v_mul_f32_e32 v10, v57, v12
	v_mul_f32_e32 v11, v58, v12
	v_mul_f32_e32 v13, v59, v12
	global_store_dwordx2 v[4:5], v[6:7], off offset:144
	s_waitcnt vmcnt(15)
	v_mov_b32_e32 v8, v114
	v_mov_b32_e32 v9, v115
	v_lshlrev_b32_e32 v6, 16, v8
	v_and_b32_e32 v7, 0xffff0000, v8
	v_lshlrev_b32_e32 v8, 16, v9
	v_and_b32_e32 v9, 0xffff0000, v9
	v_mul_f32_e32 v0, v0, v6
	v_mul_f32_e32 v6, v10, v7
	v_mul_f32_e32 v7, v11, v8
	v_mul_f32_e32 v8, v13, v9
	v_cvt_pk_bf16_f32 v6, v0, v6
	v_cvt_pk_bf16_f32 v7, v7, v8
	v_mul_f32_e32 v0, v60, v12
	v_mul_f32_e32 v10, v61, v12
	v_mul_f32_e32 v11, v62, v12
	v_mul_f32_e32 v13, v63, v12
	global_store_dwordx2 v[4:5], v[6:7], off offset:160
	s_waitcnt vmcnt(15)
	v_mov_b32_e32 v8, v116
	v_mov_b32_e32 v9, v117
	v_lshlrev_b32_e32 v6, 16, v8
	v_and_b32_e32 v7, 0xffff0000, v8
	v_lshlrev_b32_e32 v8, 16, v9
	v_and_b32_e32 v9, 0xffff0000, v9
	v_mul_f32_e32 v0, v0, v6
	v_mul_f32_e32 v6, v10, v7
	v_mul_f32_e32 v7, v11, v8
	v_mul_f32_e32 v8, v13, v9
	v_cvt_pk_bf16_f32 v6, v0, v6
	v_cvt_pk_bf16_f32 v7, v7, v8
	v_mul_f32_e32 v0, v32, v12
	v_mul_f32_e32 v10, v33, v12
	v_mul_f32_e32 v11, v34, v12
	v_mul_f32_e32 v13, v35, v12
	global_store_dwordx2 v[4:5], v[6:7], off offset:176
	s_waitcnt vmcnt(15)
	v_mov_b32_e32 v8, v118
	v_mov_b32_e32 v9, v119
	v_lshlrev_b32_e32 v6, 16, v8
	v_and_b32_e32 v7, 0xffff0000, v8
	v_lshlrev_b32_e32 v8, 16, v9
	v_and_b32_e32 v9, 0xffff0000, v9
	v_mul_f32_e32 v0, v0, v6
	v_mul_f32_e32 v6, v10, v7
	v_mul_f32_e32 v7, v11, v8
	v_mul_f32_e32 v8, v13, v9
	v_cvt_pk_bf16_f32 v6, v0, v6
	v_cvt_pk_bf16_f32 v7, v7, v8
	v_mul_f32_e32 v0, v36, v12
	v_mul_f32_e32 v10, v37, v12
	v_mul_f32_e32 v11, v38, v12
	v_mul_f32_e32 v13, v39, v12
	global_store_dwordx2 v[4:5], v[6:7], off offset:192
	s_waitcnt vmcnt(15)
	v_mov_b32_e32 v8, v120
	v_mov_b32_e32 v9, v121
	v_lshlrev_b32_e32 v6, 16, v8
	v_and_b32_e32 v7, 0xffff0000, v8
	v_lshlrev_b32_e32 v8, 16, v9
	v_and_b32_e32 v9, 0xffff0000, v9
	v_mul_f32_e32 v0, v0, v6
	v_mul_f32_e32 v6, v10, v7
	v_mul_f32_e32 v7, v11, v8
	v_mul_f32_e32 v8, v13, v9
	v_cvt_pk_bf16_f32 v6, v0, v6
	v_cvt_pk_bf16_f32 v7, v7, v8
	v_mul_f32_e32 v0, v40, v12
	v_mul_f32_e32 v10, v41, v12
	v_mul_f32_e32 v11, v42, v12
	global_store_dwordx2 v[4:5], v[6:7], off offset:208
	v_mul_f32_e32 v13, v43, v12
	s_waitcnt vmcnt(15)
	v_mov_b32_e32 v8, v122
	v_mov_b32_e32 v9, v123
	v_lshlrev_b32_e32 v6, 16, v8
	v_and_b32_e32 v7, 0xffff0000, v8
	v_lshlrev_b32_e32 v8, 16, v9
	v_and_b32_e32 v9, 0xffff0000, v9
	v_mul_f32_e32 v0, v0, v6
	v_mul_f32_e32 v6, v10, v7
	v_mul_f32_e32 v7, v11, v8
	v_mul_f32_e32 v8, v13, v9
	v_cvt_pk_bf16_f32 v6, v0, v6
	v_cvt_pk_bf16_f32 v7, v7, v8
	v_mul_f32_e32 v8, v45, v12
	v_mul_f32_e32 v10, v47, v12
	global_store_dwordx2 v[4:5], v[6:7], off offset:224
	v_mul_f32_e32 v0, v44, v12
	v_mul_f32_e32 v9, v46, v12
	s_waitcnt vmcnt(15)
	v_mov_b32_e32 v2, v124
	v_mov_b32_e32 v3, v125
	v_lshlrev_b32_e32 v6, 16, v2
	v_and_b32_e32 v2, 0xffff0000, v2
	v_lshlrev_b32_e32 v7, 16, v3
	v_and_b32_e32 v3, 0xffff0000, v3
	v_mul_f32_e32 v2, v8, v2
	v_mul_f32_e32 v3, v10, v3
	v_mul_f32_e32 v0, v0, v6
	v_mul_f32_e32 v6, v9, v7
	v_cvt_pk_bf16_f32 v2, v0, v2
	v_cvt_pk_bf16_f32 v3, v6, v3
	global_store_dwordx2 v[4:5], v[2:3], off offset:240
	s_barrier
	s_branch .LBB0_833
